# dil KV loop K-norm: sum of squares as one pk_mul + 3 pk_fma chain (8 v_mov and 2 adds removed), never-taken rsq denormal guard removed (input >= eps)
# baseline (speedup 1.0000x reference)
; #define LAS __attribute__((address_space(3)))
; template <int K> __device__ __forceinline__ float swz_f(float v) { return __uint_as_float(swz_u<K>(__float_as_uint(v))); }
; #define UNPACK8(v, k) const float k##0 = blo(v.x), k##1 = bhi(v.x), k##2 = blo(v.y), k##3 = bhi(v.y), k##4 = blo(v.z), k##5 = bhi(v.z), k##6 = blo(v.w), k##7 = bhi(v.w)
; __device__ __forceinline__ unsigned cvtpk(float lo, float hi) { f32x2_t v = {lo, hi}; bf16x2_t b = __builtin_convertvector(v, bf16x2_t); return __builtin_bit_cast(unsigned, b); }
; template <bool NORM> __device__ __forceinline__ void kv_store(u32x4 kc, u32x4 vc, const float (&g)[8], LAS unsigned char* ksb, LAS unsigned char* vtb, int tid) {
;     ...
;     if (NORM) { UNPACK8(kc, k); float ss = (k0 * k0 + k1 * k1) + (k2 * k2 + k3 * k3) + (k4 * k4 + k5 * k5) + (k6 * k6 + k7 * k7);
;         ss += swz_f<1>(ss); ss += swz_f<2>(ss); ss += swz_f<4>(ss);
;         const float rs = rsqrtf(ss * (1.f / 64.f) + EPS);
;         kc.x = cvtpk(k0 * rs * g[0], k1 * rs * g[1]); kc.y = cvtpk(k2 * rs * g[2], k3 * rs * g[3]); kc.z = cvtpk(k4 * rs * g[4], k5 * rs * g[5]); kc.w = cvtpk(k6 * rs * g[6], k7 * rs * g[7]); }
;     *(LAS u32x4*)(ksb + kl * KSB + ch * 16) = kc;
;     LAS unsigned short* vp = (LAS unsigned short*)(vtb + (8 * ch) * VTB + kl * 2);
;     vp[0 * (VTB / 2)] = (unsigned short)(vc.x & 0xffffu); vp[1 * (VTB / 2)] = (unsigned short)(vc.x >> 16);
;     vp[2 * (VTB / 2)] = (unsigned short)(vc.y & 0xffffu); vp[3 * (VTB / 2)] = (unsigned short)(vc.y >> 16);
;     vp[4 * (VTB / 2)] = (unsigned short)(vc.z & 0xffffu); vp[5 * (VTB / 2)] = (unsigned short)(vc.z >> 16);
;     vp[6 * (VTB / 2)] = (unsigned short)(vc.w & 0xffffu); vp[7 * (VTB / 2)] = (unsigned short)(vc.w >> 16);
; }
.LBB0_863:
	s_waitcnt vmcnt(1)
	v_and_b32_e32 v53, 0xffff0000, v5
	v_and_b32_e32 v51, 0xffff0000, v4
	v_lshlrev_b32_e32 v52, 16, v5
	v_lshlrev_b32_e32 v50, 16, v4
	v_pk_mul_f32 v[48:49], v[50:51], v[50:51]
	v_and_b32_e32 v57, 0xffff0000, v2
	v_and_b32_e32 v55, 0xffff0000, v3
	v_lshlrev_b32_e32 v54, 16, v3
	v_lshlrev_b32_e32 v56, 16, v2
	v_pk_fma_f32 v[48:49], v[52:53], v[52:53], v[48:49]
	s_mul_i32 s0, s6, 0x2400
	s_mul_i32 s98, s6, 0x3000
	s_add_i32 s16, s0, 0
	v_pk_fma_f32 v[48:49], v[54:55], v[54:55], v[48:49]
	v_pk_fma_f32 v[48:49], v[56:57], v[56:57], v[48:49]
	v_add_f32_e32 v48, v48, v49
	s_lshl_b32 s0, s6, 9
	s_sub_i32 s9, s16, s0
	s_cmp_ge_u32 s13, s24
	s_cselect_b64 s[4:5], -1, 0
	s_nop 1
	v_add_f32_dpp v48, v48, v48 quad_perm:[1,0,3,2] row_mask:0xf bank_mask:0xf
	s_nop 1
	v_add_f32_dpp v48, v48, v48 quad_perm:[2,3,0,1] row_mask:0xf bank_mask:0xf
	s_nop 1
	v_add_f32_dpp v48, v48, v48 row_half_mirror row_mask:0xf bank_mask:0xf
	v_fmamk_f32 v48, v48, 0x3c800000, v139
	v_rsq_f32_e32 v58, v48
	s_nop 0
	v_pk_mul_f32 v[48:49], v[58:59], v[56:57] op_sel_hi:[0,1]
	v_pk_mul_f32 v[54:55], v[58:59], v[54:55] op_sel_hi:[0,1]
	v_pk_mul_f32 v[50:51], v[58:59], v[50:51] op_sel_hi:[0,1]
	v_pk_mul_f32 v[52:53], v[58:59], v[52:53] op_sel_hi:[0,1]
	v_pk_mul_f32 v[48:49], v[14:15], v[48:49]
	v_pk_mul_f32 v[54:55], v[96:97], v[54:55]
	v_pk_mul_f32 v[50:51], v[98:99], v[50:51]
	v_pk_mul_f32 v[52:53], v[100:101], v[52:53]
	v_cvt_pk_bf16_f32 v48, v48, v49
	v_cvt_pk_bf16_f32 v49, v54, v55
	v_cvt_pk_bf16_f32 v50, v50, v51
	v_cvt_pk_bf16_f32 v51, v52, v53
	v_add3_u32 v52, s16, v95, v108
	ds_write_b128 v52, v[48:51]
	v_add_u32_e32 v48, s98, v110
	s_and_b64 vcc, exec, s[4:5]
	s_waitcnt vmcnt(0)
	ds_write_b128 v48, v[6:9] offset:18432
	s_waitcnt lgkmcnt(0)
	s_barrier
	s_cbranch_vccnz .LBB0_867
	v_add_u32_e32 v48, s43, v114
	v_cmp_lt_i32_e32 vcc, -1, v48
	v_cmp_gt_i32_e64 s[0:1], s30, v48
	s_and_b64 s[26:27], vcc, s[0:1]
	v_mov_b32_e32 v9, 0
	v_mov_b32_e32 v5, 0
	v_mov_b32_e32 v4, 0
	v_mov_b32_e32 v3, 0
	v_mov_b32_e32 v2, 0
	v_mov_b32_e32 v8, 0
	v_mov_b32_e32 v7, 0
	v_mov_b32_e32 v6, 0
	s_and_saveexec_b64 s[0:1], s[26:27]
	s_cbranch_execz .LBB0_866
	v_mad_u64_u32 v[2:3], s[26:27], s44, v48, 0
	v_lshlrev_b64 v[2:3], 1, v[2:3]
	v_lshl_add_u64 v[4:5], v[102:103], 0, v[2:3]
	v_lshl_add_u64 v[6:7], v[104:105], 0, v[2:3]
	global_load_dwordx4 v[2:5], v[4:5], off
	s_nop 0
	global_load_dwordx4 v[6:9], v[6:7], off
